# v30: P0 weight conversion: removed the never-consumed clamped prefetches (30 loads per wave) and skipped the second-item fetch on waves with one item
# speedup vs baseline: 1.0037x; 1.0037x over previous
; #define LAS __attribute__((address_space(3)))
; #define CONV_LANDED(s_) do { asm volatile("" :: "v"((s_).v[0]), "v"((s_).v[1]), "v"((s_).v[2]), "v"((s_).v[3]), "v"((s_).v[4]), "v"((s_).v[5]), "v"((s_).v[6]), "v"((s_).v[7]), "v"((s_).g0), "v"((s_).g1)); } while (0)
; #define CONV_JOB(it_) conv_job<LIST>((it_) < n ? (it_) : n - 1, P)
; __device__ __forceinline__ void conv_fetch(const ConvJob& j, int lane, ConvSet& s) {
;     const int k0 = 64 * j.kb; int cnt; const int src = vgroup_src(j.kind, j.g, cnt);
;     const int ks = lane >> 3, n4 = (lane & 7) * 4, c = lane & 7; const bool okc = n4 < cnt;
;     const float* gp = j.gain ? j.gain + k0 + 8 * c : j.W;
;     s.g0 = *(const f32x4*)gp; s.g1 = *(const f32x4*)(gp + 4);
;     const float* wp = j.W + (size_t)(k0 + ks) * j.Norig + src + (okc ? n4 : 0);
; #pragma unroll
;     for (int i = 0; i < 8; ++i) s.v[i] = *(const f32x4*)(wp + (size_t)(8 * i) * j.Norig);
; }
; template <int LIST> __device__ __forceinline__ void convert_list(int first, int stride, const Params& P, LAS float* scr, int lane) {
;     constexpr int n = conv_count<LIST>();
;     if (first >= n) return;
;     ConvSet A, B, C;
;     ...
;     conv_fetch(CONV_JOB(first), lane, A); conv_fetch(CONV_JOB(first + stride), lane, B);
;     CONV_LANDED(A); CONV_LANDED(B);
.LBB0_13:
	s_lshr_b32 s3, s3, 6
	s_add_u32 s26, s50, 0xb00000
	s_addc_u32 s27, s51, 0
	s_add_u32 s0, s50, 0x1080000
	s_addc_u32 s1, s51, 0
	v_writelane_b32 v252, s0, 3
	v_and_b32_e32 v198, 63, v0
	s_nop 0
	v_writelane_b32 v252, s1, 4
	s_add_u32 s0, s50, 0x1e00000
	s_addc_u32 s1, s51, 0
	v_writelane_b32 v252, s0, 5
	s_nop 1
	v_writelane_b32 v252, s1, 6
	s_add_u32 s0, s50, 0x2200000
	s_addc_u32 s1, s51, 0
	v_writelane_b32 v252, s0, 7
	s_nop 1
	v_writelane_b32 v252, s1, 8
	s_add_u32 s0, s50, 0x2400000
	s_addc_u32 s1, s51, 0
	s_add_u32 s78, s68, 0xf940000
	s_addc_u32 s79, s69, 0
	s_lshl_b32 s76, s2, 3
	s_add_i32 s70, s3, s76
	s_lshl_b32 s92, s71, 3
	v_writelane_b32 v252, s0, 9
	s_cmp_eq_u32 s94, 0
	s_nop 0
	v_writelane_b32 v252, s1, 10
	s_cselect_b64 s[0:1], -1, 0
	s_cmp_eq_u32 s95, 12
	s_cselect_b64 s[4:5], -1, 0
	v_writelane_b32 v252, s3, 11
	s_and_b64 s[0:1], s[0:1], s[4:5]
	v_writelane_b32 v252, s0, 12
	s_cmp_lt_i32 s94, 1
	s_nop 0
	v_writelane_b32 v252, s1, 13
	s_cselect_b64 s[0:1], -1, 0
	s_cmp_gt_i32 s95, 0
	s_cselect_b64 s[4:5], -1, 0
	s_and_b64 s[4:5], s[0:1], s[4:5]
	s_andn2_b64 vcc, exec, s[4:5]
	v_writelane_b32 v252, s78, 14
	s_nop 1
	v_writelane_b32 v252, s79, 15
	s_cbranch_vccnz .LBB0_262
	v_readlane_b32 s0, v252, 12
	v_readlane_b32 s1, v252, 13
	s_xor_b64 s[28:29], s[0:1], -1
	v_readlane_b32 s0, v252, 11
	s_lshl_b32 s0, s0, 14
	s_add_i32 s3, s0, 0
	s_cmpk_lt_i32 s70, 0xb00
	s_cselect_b64 s[6:7], -1, 0
	s_cmpk_gt_i32 s70, 0xaff
	s_cbranch_scc1 .LBB0_21
	s_mul_hi_i32 s0, s70, 0x2e8ba2e9
	s_lshr_b32 s1, s0, 31
	s_ashr_i32 s0, s0, 5
	s_add_i32 s0, s0, s1
	s_mul_i32 s1, s0, 0xb0
	s_sub_i32 s1, s70, s1
	s_lshl_b32 s24, s0, 6
	s_bfe_i32 s0, s1, 0x10002
	s_lshl_b32 s25, s1, 4
	s_and_b32 s0, s0, 0xb00
	s_and_b32 s25, s25, 0xffffff80
	s_lshl_b32 s1, s1, 5
	s_add_i32 s0, s0, s25
	s_and_b32 s1, s1, 0x60
	s_or_b32 s30, s0, s1
	s_cmp_eq_u64 s[18:19], 0
	s_cselect_b64 s[0:1], -1, 0
	s_ashr_i32 s25, s24, 31
	s_lshl_b64 s[34:35], s[24:25], 2
	v_and_b32_e32 v85, 7, v0
	s_add_u32 s34, s18, s34
	v_lshrrev_b32_e32 v130, 3, v198
	s_addc_u32 s35, s19, s35
	v_mov_b32_e32 v123, 0
	v_lshlrev_b32_e32 v122, 5, v85
	v_or_b32_e32 v12, s24, v130
	s_movk_i32 s24, 0x5800
	v_mov_b64_e32 v[10:11], s[20:21]
	v_lshl_add_u64 v[2:3], s[34:35], 0, v[122:123]
	v_mad_i64_i32 v[10:11], s[34:35], v12, s24, v[10:11]
	s_ashr_i32 s31, s30, 31
	v_lshl_add_u64 v[10:11], s[30:31], 2, v[10:11]
	s_add_i32 s30, s92, s70
	s_min_i32 s30, s30, 0xaff
	s_mul_hi_i32 s31, s30, 0x2e8ba2e9
	v_lshlrev_b32_e32 v82, 4, v85
	v_mov_b32_e32 v83, v123
	s_lshr_b32 s75, s31, 31
	s_ashr_i32 s31, s31, 5
	v_lshl_add_u64 v[18:19], v[10:11], 0, v[82:83]
	s_mov_b32 s25, 0x2c000
	s_add_i32 s31, s31, s75
	v_add_co_u32_e32 v10, vcc, s25, v18
	s_mul_i32 s75, s31, 0xb0
	s_nop 0
	v_addc_co_u32_e32 v11, vcc, 0, v19, vcc
	s_mov_b32 s33, 0x58000
	s_sub_i32 s75, s30, s75
	v_add_co_u32_e32 v20, vcc, s33, v18
	s_lshl_b32 s30, s31, 6
	s_bfe_i32 s31, s75, 0x10002
	s_lshl_b32 s77, s75, 4
	v_addc_co_u32_e32 v21, vcc, 0, v19, vcc
	s_mov_b32 s34, 0x84000
	s_and_b32 s31, s31, 0xb00
	s_and_b32 s77, s77, 0xffffff80
	s_lshl_b32 s75, s75, 5
	v_add_co_u32_e32 v22, vcc, s34, v18
	s_add_i32 s31, s31, s77
	s_and_b32 s75, s75, 0x60
	v_addc_co_u32_e32 v23, vcc, 0, v19, vcc
	s_mov_b32 s35, 0xb0000
	s_or_b32 s78, s31, s75
	s_ashr_i32 s31, s30, 31
	v_add_co_u32_e32 v24, vcc, s35, v18
	s_lshl_b64 s[80:81], s[30:31], 2
	s_nop 0
	v_addc_co_u32_e32 v25, vcc, 0, v19, vcc
	s_mov_b32 s72, 0xdc000
	s_add_u32 s80, s18, s80
	v_add_co_u32_e32 v26, vcc, s72, v18
	s_addc_u32 s81, s19, s81
	v_mov_b32_e32 v32, s21
	v_mov_b32_e32 v33, s20
	v_addc_co_u32_e32 v27, vcc, 0, v19, vcc
	s_mov_b32 s73, 0x108000
	v_lshl_add_u64 v[30:31], s[80:81], 0, v[122:123]
	v_cndmask_b32_e64 v7, v3, v32, s[0:1]
	v_cndmask_b32_e64 v6, v2, v33, s[0:1]
	v_add_co_u32_e32 v28, vcc, s73, v18
	v_cndmask_b32_e64 v31, v31, v32, s[0:1]
	v_cndmask_b32_e64 v30, v30, v33, s[0:1]
	v_or_b32_e32 v34, s30, v130
	v_mov_b64_e32 v[32:33], s[20:21]
	v_addc_co_u32_e32 v29, vcc, 0, v19, vcc
	s_mov_b32 s74, 0x134000
	v_mad_i64_i32 v[32:33], s[30:31], v34, s24, v[32:33]
	s_ashr_i32 s79, s78, 31
	global_load_dwordx4 v[2:5], v[6:7], off offset:16 nt
	s_nop 0
	global_load_dwordx4 v[6:9], v[6:7], off nt
	s_nop 0
	global_load_dwordx4 v[14:17], v[18:19], off nt
	s_nop 0
	global_load_dwordx4 v[10:13], v[10:11], off nt
	v_add_co_u32_e32 v18, vcc, s74, v18
	v_lshl_add_u64 v[32:33], s[78:79], 2, v[32:33]
	s_nop 0
	v_addc_co_u32_e32 v19, vcc, 0, v19, vcc
	v_lshl_add_u64 v[32:33], v[32:33], 0, v[82:83]
	v_add_co_u32_e32 v34, vcc, s25, v32
	v_add_u32_e32 v82, s3, v82
	s_nop 0
	v_addc_co_u32_e32 v35, vcc, 0, v33, vcc
	v_add_co_u32_e32 v36, vcc, s33, v32
	v_mul_u32_u24_e32 v83, 0x84, v130
	s_nop 0
	v_addc_co_u32_e32 v37, vcc, 0, v33, vcc
	v_add_co_u32_e32 v38, vcc, s34, v32
	v_lshl_add_u64 v[124:125], s[18:19], 0, v[122:123]
	s_nop 0
	v_addc_co_u32_e32 v39, vcc, 0, v33, vcc
	v_add_co_u32_e32 v42, vcc, s35, v32
	s_add_i32 s18, s2, s71
	s_nop 0
	v_addc_co_u32_e32 v43, vcc, 0, v33, vcc
	v_add_co_u32_e32 v46, vcc, s72, v32
	v_lshlrev_b32_e32 v84, 2, v85
	s_nop 0
	v_addc_co_u32_e32 v47, vcc, 0, v33, vcc
	v_add_co_u32_e32 v50, vcc, s73, v32
	v_mul_u32_u24_e32 v86, 0x420, v85
	s_nop 0
	v_addc_co_u32_e32 v51, vcc, 0, v33, vcc
	v_add_co_u32_e32 v54, vcc, s74, v32
	v_lshlrev_b32_e32 v87, 2, v130
	s_nop 0
	v_addc_co_u32_e32 v55, vcc, 0, v33, vcc
	global_load_dwordx4 v[78:81], v[20:21], off nt
	global_load_dwordx4 v[74:77], v[22:23], off nt
	global_load_dwordx4 v[70:73], v[24:25], off nt
	global_load_dwordx4 v[66:69], v[26:27], off nt
	global_load_dwordx4 v[62:65], v[28:29], off nt
	global_load_dwordx4 v[58:61], v[18:19], off nt
	s_nop 0
	s_add_i32 s100, s92, s70
	s_cmpk_lt_i32 s100, 0xb00
	s_cbranch_scc0 .Lp0_skipB
	global_load_dwordx4 v[18:21], v[30:31], off offset:16 nt
	global_load_dwordx4 v[22:25], v[30:31], off nt
	global_load_dwordx4 v[26:29], v[32:33], off nt
	s_nop 0
	global_load_dwordx4 v[30:33], v[34:35], off nt
	s_nop 0
	global_load_dwordx4 v[34:37], v[36:37], off nt
	s_nop 0
	global_load_dwordx4 v[38:41], v[38:39], off nt
	s_nop 0
	global_load_dwordx4 v[42:45], v[42:43], off nt
	s_nop 0
	global_load_dwordx4 v[46:49], v[46:47], off nt
	s_nop 0
	global_load_dwordx4 v[50:53], v[50:51], off nt
	s_nop 0
	global_load_dwordx4 v[54:57], v[54:55], off nt
.Lp0_skipB:
	v_add_u32_e32 v132, v82, v83
	s_lshl_b32 s18, s18, 3
	v_readlane_b32 s19, v252, 11
	v_lshlrev_b32_e32 v82, 3, v85
	v_add3_u32 v131, s3, v86, v87
	v_lshlrev_b32_e32 v122, 2, v84
	s_lshl_b32 s75, s71, 4
	s_mul_i32 s77, s71, 24
	s_add_i32 s78, s19, s18
	s_lshl_b32 s79, s71, 5
	v_lshlrev_b32_e32 v126, 1, v82
	s_mov_b32 s81, s70
	v_or_b32_e32 v133, 8, v130
	v_or_b32_e32 v134, 16, v130
	v_or_b32_e32 v135, 24, v130
	s_waitcnt vmcnt(10)
	s_waitcnt vmcnt(0)
	s_branch .LBB0_17

; #define LAS __attribute__((address_space(3)))
; __device__ __forceinline__ unsigned cvtpk(float lo, float hi) { f32x2_t v = {lo, hi}; bf16x2_t b = __builtin_convertvector(v, bf16x2_t); return __builtin_bit_cast(unsigned, b); }
; #define LDS_WAIT() asm volatile("s_waitcnt lgkmcnt(0)" ::: "memory")
; #define CONV_JOB(it_) conv_job<LIST>((it_) < n ? (it_) : n - 1, P)
; __device__ __forceinline__ void conv_emit(const ConvJob& j, int lane, const ConvSet& s, LAS float* scr) {
;     const int k0 = 64 * j.kb; int cnt; (void)vgroup_src(j.kind, j.g, cnt);
;     const int ks = lane >> 3, n4 = (lane & 7) * 4, c = lane & 7; const bool okc = n4 < cnt;
;     const f32x4 one = (f32x4){1.f, 1.f, 1.f, 1.f}; const f32x4 g0 = j.gain ? s.g0 : one, g1 = j.gain ? s.g1 : one;
; #pragma unroll
;     for (int i = 0; i < 8; ++i) { LAS float* sp = scr + (8 * i + ks) * 33 + n4;
; #pragma unroll
;         for (int e = 0; e < 4; ++e) sp[e] = okc ? s.v[i][e] : 0.f; }
;     LDS_WAIT(); asm volatile("" ::: "memory");
; #pragma unroll
;     for (int q = 0; q < 4; ++q) { const int nn = (lane >> 3) + 8 * q; const LAS float* sr = scr + (8 * c) * 33 + nn;
;         u32x4 o; o.x = cvtpk(sr[0 * 33] * g0[0], sr[1 * 33] * g0[1]); o.y = cvtpk(sr[2 * 33] * g0[2], sr[3 * 33] * g0[3]); o.z = cvtpk(sr[4 * 33] * g1[0], sr[5 * 33] * g1[1]); o.w = cvtpk(sr[6 * 33] * g1[2], sr[7 * 33] * g1[3]);
;         *(u32x4*)(j.WT + (size_t)(j.g * 32 + nn) * j.K + k0 + 8 * c) = o; }
;     LDS_WAIT(); asm volatile("" ::: "memory");
; }
; template <int LIST> __device__ __forceinline__ void convert_list(int first, int stride, const Params& P, LAS float* scr, int lane) {
;     ...
;     for (int it = first; it < n; it += 3 * stride) {
;         conv_fetch(CONV_JOB(it + 2 * stride), lane, C); conv_emit(CONV_JOB(it), lane, A, scr);
;         conv_fetch(CONV_JOB(it + 3 * stride), lane, A); if (it + stride < n) conv_emit(CONV_JOB(it + stride), lane, B, scr);
.LBB0_17:
	s_add_i32 s80, s81, s75
	s_cmpk_lt_i32 s80, 0xb00
	s_cselect_b64 s[18:19], -1, 0
	s_and_b64 s[30:31], s[18:19], exec
	s_cselect_b32 s30, s80, 0xaff
	s_mul_hi_i32 s31, s30, 0x2e8ba2e9
	s_lshr_b32 s82, s31, 31
	s_ashr_i32 s31, s31, 5
	s_add_i32 s31, s31, s82
	s_mul_i32 s82, s31, 0xb0
	s_sub_i32 s82, s30, s82
	s_lshl_b32 s30, s31, 6
	s_bfe_i32 s31, s82, 0x10002
	s_lshl_b32 s83, s82, 4
	s_and_b32 s31, s31, 0xb00
	s_and_b32 s83, s83, 0xffffff80
	s_lshl_b32 s82, s82, 5
	s_add_i32 s31, s31, s83
	s_and_b32 s82, s82, 0x60
	s_or_b32 s82, s31, s82
	s_ashr_i32 s31, s30, 31
	s_waitcnt vmcnt(31)
	v_or_b32_e32 v90, s30, v130
	v_mov_b64_e32 v[128:129], s[20:21]
	v_lshl_add_u64 v[82:83], s[30:31], 2, v[124:125]
	v_mad_i64_i32 v[90:91], s[30:31], v90, s24, v[128:129]
	s_ashr_i32 s83, s82, 31
	v_lshl_add_u64 v[90:91], s[82:83], 2, v[90:91]
	s_waitcnt vmcnt(26)
	v_lshl_add_u64 v[106:107], v[90:91], 0, v[122:123]
	v_add_co_u32_e32 v94, vcc, s25, v106
	v_mov_b32_e32 v150, s21
	s_nop 0
	v_addc_co_u32_e32 v95, vcc, 0, v107, vcc
	v_add_co_u32_e32 v98, vcc, s33, v106
	v_mov_b32_e32 v151, s20
	s_nop 0
	v_addc_co_u32_e32 v99, vcc, 0, v107, vcc
	v_add_co_u32_e32 v102, vcc, s34, v106
	v_cndmask_b32_e64 v87, v83, v150, s[0:1]
	s_nop 0
	v_addc_co_u32_e32 v103, vcc, 0, v107, vcc
	v_add_co_u32_e32 v108, vcc, s35, v106
	v_cndmask_b32_e64 v86, v82, v151, s[0:1]
	s_nop 0
	v_addc_co_u32_e32 v109, vcc, 0, v107, vcc
	s_waitcnt vmcnt(24)
	v_add_co_u32_e32 v114, vcc, s72, v106
	v_add_u32_e32 v136, 0x420, v132
	s_nop 0
	v_addc_co_u32_e32 v115, vcc, 0, v107, vcc
	v_add_co_u32_e32 v116, vcc, s73, v106
	v_add_u32_e32 v137, 0x428, v132
	s_nop 0
	v_addc_co_u32_e32 v117, vcc, 0, v107, vcc
	v_add_co_u32_e32 v138, vcc, s74, v106
	s_nop 0
	s_nop 0
	s_nop 0
	s_nop 0
	s_nop 0
	v_addc_co_u32_e32 v139, vcc, 0, v107, vcc
	s_nop 0
	s_waitcnt vmcnt(25)
	ds_write2_b32 v132, v14, v15 offset1:1
	ds_write2_b32 v132, v16, v17 offset0:2 offset1:3
	s_waitcnt vmcnt(24)
	ds_write2_b32 v136, v10, v11 offset1:1
	ds_write2_b32 v137, v12, v13 offset1:1
	s_nop 0
	v_add_u32_e32 v138, 0x840, v132
	v_add_u32_e32 v139, 0x848, v132
	v_add_u32_e32 v140, 0xc60, v132
	v_add_u32_e32 v141, 0xc68, v132
	v_add_u32_e32 v142, 0x1080, v132
	v_add_u32_e32 v143, 0x1088, v132
	v_add_u32_e32 v144, 0x14a0, v132
	v_add_u32_e32 v145, 0x14a8, v132
	v_add_u32_e32 v146, 0x18c0, v132
	v_add_u32_e32 v147, 0x18c8, v132
	v_add_u32_e32 v148, 0x1ce0, v132
	v_add_u32_e32 v149, 0x1ce8, v132
	s_waitcnt vmcnt(25)
	ds_write2_b32 v138, v78, v79 offset1:1
	ds_write2_b32 v139, v80, v81 offset1:1
	s_waitcnt vmcnt(24)
	ds_write2_b32 v140, v74, v75 offset1:1
	ds_write2_b32 v141, v76, v77 offset1:1
	s_waitcnt vmcnt(23)
	ds_write2_b32 v142, v70, v71 offset1:1
	ds_write2_b32 v143, v72, v73 offset1:1
	s_waitcnt vmcnt(22)
	ds_write2_b32 v144, v66, v67 offset1:1
	ds_write2_b32 v145, v68, v69 offset1:1
	s_waitcnt vmcnt(21)
	ds_write2_b32 v146, v62, v63 offset1:1
	ds_write2_b32 v147, v64, v65 offset1:1
	s_waitcnt vmcnt(20)
	ds_write2_b32 v148, v58, v59 offset1:1
	ds_write2_b32 v149, v60, v61 offset1:1
	s_waitcnt lgkmcnt(0)
	ds_read2_b32 v[12:13], v131 offset1:8
	ds_read2_b32 v[16:17], v131 offset0:33 offset1:41
	ds_read2_b32 v[58:59], v131 offset0:66 offset1:74
	ds_read2_b32 v[60:61], v131 offset0:99 offset1:107
	ds_read2_b32 v[62:63], v131 offset0:132 offset1:140
	ds_read2_b32 v[64:65], v131 offset0:165 offset1:173
	ds_read2_b32 v[66:67], v131 offset0:198 offset1:206
	ds_read2_b32 v[68:69], v131 offset0:231 offset1:239
	s_mul_hi_i32 s30, s81, 0x2e8ba2e9
	s_lshr_b32 s31, s30, 31
	s_ashr_i32 s30, s30, 5
	v_cndmask_b32_e64 v9, v9, 1.0, s[0:1]
	v_cndmask_b32_e64 v8, v8, 1.0, s[0:1]
	v_cndmask_b32_e64 v7, v7, 1.0, s[0:1]
	v_cndmask_b32_e64 v6, v6, 1.0, s[0:1]
	v_cndmask_b32_e64 v11, v5, 1.0, s[0:1]
	v_cndmask_b32_e64 v10, v4, 1.0, s[0:1]
	v_cndmask_b32_e64 v15, v3, 1.0, s[0:1]
	v_cndmask_b32_e64 v14, v2, 1.0, s[0:1]
	s_waitcnt lgkmcnt(7)
	v_mov_b32_e32 v2, v12
	s_waitcnt lgkmcnt(6)
	v_mov_b32_e32 v3, v16
	s_waitcnt lgkmcnt(5)
	v_mov_b32_e32 v4, v58
	s_waitcnt lgkmcnt(4)
	v_mov_b32_e32 v5, v60
	s_add_i32 s30, s30, s31
	v_pk_mul_f32 v[2:3], v[6:7], v[2:3]
	v_pk_mul_f32 v[4:5], v[8:9], v[4:5]
	s_mul_i32 s31, s30, 0xb0
	v_cvt_pk_bf16_f32 v2, v2, v3
	v_cvt_pk_bf16_f32 v3, v4, v5
	s_waitcnt lgkmcnt(3)
	v_mov_b32_e32 v4, v62
	s_waitcnt lgkmcnt(2)
	v_mov_b32_e32 v5, v64
	s_waitcnt lgkmcnt(1)
	v_mov_b32_e32 v70, v66
	s_waitcnt lgkmcnt(0)
	v_mov_b32_e32 v71, v68
	s_sub_i32 s82, s81, s31
	v_pk_mul_f32 v[4:5], v[14:15], v[4:5]
	v_pk_mul_f32 v[70:71], v[10:11], v[70:71]
	s_lshl_b32 s82, s82, 5
	v_cvt_pk_bf16_f32 v4, v4, v5
	v_cvt_pk_bf16_f32 v5, v70, v71
	v_or_b32_e32 v70, s82, v130
	s_lshl_b32 s30, s30, 6
	v_ashrrev_i32_e32 v71, 31, v70
	s_ashr_i32 s31, s30, 31
	v_lshlrev_b64 v[70:71], 11, v[70:71]
	v_lshl_add_u64 v[70:71], s[50:51], 0, v[70:71]
	s_lshl_b64 s[30:31], s[30:31], 1
	v_lshl_add_u64 v[70:71], v[70:71], 0, s[30:31]
	v_mov_b32_e32 v127, v123
	v_lshl_add_u64 v[70:71], v[70:71], 0, v[126:127]
	v_mov_b32_e32 v16, v13
	v_mov_b32_e32 v60, v59
	global_store_dwordx4 v[70:71], v[2:5], off
	v_mov_b32_e32 v64, v63
	v_mov_b32_e32 v68, v67
	v_pk_mul_f32 v[2:3], v[6:7], v[16:17]
	v_pk_mul_f32 v[4:5], v[8:9], v[60:61]
	v_cvt_pk_bf16_f32 v2, v2, v3
	v_cvt_pk_bf16_f32 v3, v4, v5
	v_pk_mul_f32 v[4:5], v[14:15], v[64:65]
	v_pk_mul_f32 v[12:13], v[10:11], v[68:69]
	v_cvt_pk_bf16_f32 v4, v4, v5
	v_cvt_pk_bf16_f32 v5, v12, v13
	v_or_b32_e32 v12, s82, v133
	v_ashrrev_i32_e32 v13, 31, v12
	v_lshlrev_b64 v[12:13], 11, v[12:13]
	v_lshl_add_u64 v[12:13], s[50:51], 0, v[12:13]
	v_lshl_add_u64 v[12:13], v[12:13], 0, s[30:31]
	v_lshl_add_u64 v[12:13], v[12:13], 0, v[126:127]
	global_store_dwordx4 v[12:13], v[2:5], off
	ds_read2_b32 v[16:17], v131 offset0:16 offset1:24
	ds_read2_b32 v[58:59], v131 offset0:49 offset1:57
	ds_read2_b32 v[12:13], v131 offset0:82 offset1:90
	ds_read2_b32 v[60:61], v131 offset0:115 offset1:123
	ds_read2_b32 v[62:63], v131 offset0:148 offset1:156
	ds_read2_b32 v[64:65], v131 offset0:181 offset1:189
	ds_read2_b32 v[66:67], v131 offset0:214 offset1:222
	ds_read2_b32 v[68:69], v131 offset0:247 offset1:255
	s_waitcnt lgkmcnt(7)
; #define LAS __attribute__((address_space(3)))
; __device__ __forceinline__ unsigned cvtpk(float lo, float hi) { f32x2_t v = {lo, hi}; bf16x2_t b = __builtin_convertvector(v, bf16x2_t); return __builtin_bit_cast(unsigned, b); }
; #define LDS_WAIT() asm volatile("s_waitcnt lgkmcnt(0)" ::: "memory")
; #define CONV_JOB(it_) conv_job<LIST>((it_) < n ? (it_) : n - 1, P)
; __device__ __forceinline__ void conv_emit(const ConvJob& j, int lane, const ConvSet& s, LAS float* scr) {
;     const int k0 = 64 * j.kb; int cnt; (void)vgroup_src(j.kind, j.g, cnt);
;     const int ks = lane >> 3, n4 = (lane & 7) * 4, c = lane & 7; const bool okc = n4 < cnt;
;     const f32x4 one = (f32x4){1.f, 1.f, 1.f, 1.f}; const f32x4 g0 = j.gain ? s.g0 : one, g1 = j.gain ? s.g1 : one;
; #pragma unroll
;     for (int i = 0; i < 8; ++i) { LAS float* sp = scr + (8 * i + ks) * 33 + n4;
; #pragma unroll
;         for (int e = 0; e < 4; ++e) sp[e] = okc ? s.v[i][e] : 0.f; }
;     LDS_WAIT(); asm volatile("" ::: "memory");
; #pragma unroll
;     for (int q = 0; q < 4; ++q) { const int nn = (lane >> 3) + 8 * q; const LAS float* sr = scr + (8 * c) * 33 + nn;
;         u32x4 o; o.x = cvtpk(sr[0 * 33] * g0[0], sr[1 * 33] * g0[1]); o.y = cvtpk(sr[2 * 33] * g0[2], sr[3 * 33] * g0[3]); o.z = cvtpk(sr[4 * 33] * g1[0], sr[5 * 33] * g1[1]); o.w = cvtpk(sr[6 * 33] * g1[2], sr[7 * 33] * g1[3]);
;         *(u32x4*)(j.WT + (size_t)(j.g * 32 + nn) * j.K + k0 + 8 * c) = o; }
;     LDS_WAIT(); asm volatile("" ::: "memory");
; }
; template <int LIST> __device__ __forceinline__ void convert_list(int first, int stride, const Params& P, LAS float* scr, int lane) {
;     ...
;         conv_fetch(CONV_JOB(it + 2 * stride), lane, C); conv_emit(CONV_JOB(it), lane, A, scr);
;         conv_fetch(CONV_JOB(it + 3 * stride), lane, A); if (it + stride < n) conv_emit(CONV_JOB(it + stride), lane, B, scr);
;         conv_fetch(CONV_JOB(it + 4 * stride), lane, B); if (it + 2 * stride < n) conv_emit(CONV_JOB(it + 2 * stride), lane, C, scr);
	v_mov_b32_e32 v2, v16
	s_waitcnt lgkmcnt(6)
	v_mov_b32_e32 v3, v58
	s_waitcnt lgkmcnt(5)
	v_mov_b32_e32 v4, v12
	s_waitcnt lgkmcnt(4)
	v_mov_b32_e32 v5, v60
	v_pk_mul_f32 v[2:3], v[6:7], v[2:3]
	v_pk_mul_f32 v[4:5], v[8:9], v[4:5]
	v_cvt_pk_bf16_f32 v2, v2, v3
	v_cvt_pk_bf16_f32 v3, v4, v5
	s_waitcnt lgkmcnt(3)
	v_mov_b32_e32 v4, v62
	s_waitcnt lgkmcnt(2)
	v_mov_b32_e32 v5, v64
	s_waitcnt lgkmcnt(1)
	v_mov_b32_e32 v70, v66
	s_waitcnt lgkmcnt(0)
	v_mov_b32_e32 v71, v68
	v_pk_mul_f32 v[4:5], v[14:15], v[4:5]
	v_pk_mul_f32 v[70:71], v[10:11], v[70:71]
	v_cvt_pk_bf16_f32 v4, v4, v5
	v_cvt_pk_bf16_f32 v5, v70, v71
	v_or_b32_e32 v70, s82, v134
	v_ashrrev_i32_e32 v71, 31, v70
	v_lshlrev_b64 v[70:71], 11, v[70:71]
	v_lshl_add_u64 v[70:71], s[50:51], 0, v[70:71]
	v_lshl_add_u64 v[70:71], v[70:71], 0, s[30:31]
	v_lshl_add_u64 v[70:71], v[70:71], 0, v[126:127]
	v_mov_b32_e32 v58, v17
	v_mov_b32_e32 v60, v13
	global_store_dwordx4 v[70:71], v[2:5], off
	v_mov_b32_e32 v64, v63
	v_mov_b32_e32 v68, v67
	v_pk_mul_f32 v[2:3], v[6:7], v[58:59]
	v_pk_mul_f32 v[4:5], v[8:9], v[60:61]
	v_cvt_pk_bf16_f32 v2, v2, v3
	v_cvt_pk_bf16_f32 v3, v4, v5
	v_pk_mul_f32 v[4:5], v[14:15], v[64:65]
	v_pk_mul_f32 v[6:7], v[10:11], v[68:69]
	v_cvt_pk_bf16_f32 v4, v4, v5
	v_cvt_pk_bf16_f32 v5, v6, v7
	v_or_b32_e32 v6, s82, v135
	v_ashrrev_i32_e32 v7, 31, v6
	v_lshlrev_b64 v[6:7], 11, v[6:7]
	v_lshl_add_u64 v[6:7], s[50:51], 0, v[6:7]
	v_lshl_add_u64 v[6:7], v[6:7], 0, s[30:31]
	s_add_i32 s30, s77, s81
	s_min_i32 s30, s30, 0xaff
	s_mul_hi_i32 s31, s30, 0x2e8ba2e9
	s_lshr_b32 s82, s31, 31
	s_ashr_i32 s31, s31, 5
	s_add_i32 s31, s31, s82
	s_mul_i32 s82, s31, 0xb0
	s_sub_i32 s82, s30, s82
	s_lshl_b32 s30, s31, 6
	s_bfe_i32 s31, s82, 0x10002
	s_lshl_b32 s83, s82, 4
	s_and_b32 s31, s31, 0xb00
	s_and_b32 s83, s83, 0xffffff80
	s_lshl_b32 s82, s82, 5
	s_add_i32 s31, s31, s83
	s_and_b32 s82, s82, 0x60
	v_lshl_add_u64 v[6:7], v[6:7], 0, v[126:127]
	s_or_b32 s82, s31, s82
	s_ashr_i32 s31, s30, 31
	v_or_b32_e32 v10, s30, v130
	global_store_dwordx4 v[6:7], v[2:5], off
	s_ashr_i32 s83, s82, 31
	s_waitcnt lgkmcnt(0)
	s_cmpk_gt_i32 s78, 0xaff
	v_lshl_add_u64 v[2:3], s[30:31], 2, v[124:125]
	v_mad_i64_i32 v[10:11], s[30:31], v10, s24, v[128:129]
	v_lshl_add_u64 v[10:11], s[82:83], 2, v[10:11]
	v_lshl_add_u64 v[10:11], v[10:11], 0, v[122:123]
	v_add_co_u32_e32 v12, vcc, s25, v10
	v_cndmask_b32_e64 v7, v3, v150, s[0:1]
	s_nop 0
	v_addc_co_u32_e32 v13, vcc, 0, v11, vcc
	v_add_co_u32_e32 v58, vcc, s33, v10
	v_cndmask_b32_e64 v6, v2, v151, s[0:1]
	s_nop 0
	v_addc_co_u32_e32 v59, vcc, 0, v11, vcc
	v_add_co_u32_e32 v60, vcc, s34, v10
	s_nop 0
	v_addc_co_u32_e32 v61, vcc, 0, v11, vcc
	v_add_co_u32_e32 v62, vcc, s35, v10
	s_nop 1
	v_addc_co_u32_e32 v63, vcc, 0, v11, vcc
	v_add_co_u32_e32 v64, vcc, 0xdc000, v10
	s_nop 1
	v_addc_co_u32_e32 v65, vcc, 0, v11, vcc
	v_add_co_u32_e32 v128, vcc, 0x108000, v10
	s_nop 1
	v_addc_co_u32_e32 v129, vcc, 0, v11, vcc
	v_add_co_u32_e32 v150, vcc, 0x134000, v10
	s_nop 1
	v_addc_co_u32_e32 v151, vcc, 0, v11, vcc
	s_nop 0
	s_nop 0
	s_nop 0
	s_cbranch_scc1 .LBB0_19
	s_waitcnt vmcnt(31)
	ds_write2_b32 v132, v26, v27 offset1:1
	ds_write2_b32 v132, v28, v29 offset0:2 offset1:3
	s_waitcnt vmcnt(30)
	ds_write2_b32 v136, v30, v31 offset1:1
	ds_write2_b32 v137, v32, v33 offset1:1
	s_waitcnt vmcnt(29)
	ds_write2_b32 v138, v34, v35 offset1:1
	ds_write2_b32 v139, v36, v37 offset1:1
	s_waitcnt vmcnt(28)
	ds_write2_b32 v140, v38, v39 offset1:1
	ds_write2_b32 v141, v40, v41 offset1:1
	s_waitcnt vmcnt(27)
	ds_write2_b32 v142, v42, v43 offset1:1
	ds_write2_b32 v143, v44, v45 offset1:1
	s_waitcnt vmcnt(26)
	ds_write2_b32 v144, v46, v47 offset1:1
	ds_write2_b32 v145, v48, v49 offset1:1
	s_waitcnt vmcnt(25)
	ds_write2_b32 v146, v50, v51 offset1:1
	ds_write2_b32 v147, v52, v53 offset1:1
	s_waitcnt vmcnt(24)
	ds_write2_b32 v148, v54, v55 offset1:1
	ds_write2_b32 v149, v56, v57 offset1:1
	s_waitcnt lgkmcnt(0)
	ds_read2_b32 v[28:29], v131 offset1:8
	ds_read2_b32 v[32:33], v131 offset0:33 offset1:41
	ds_read2_b32 v[34:35], v131 offset0:66 offset1:74
	ds_read2_b32 v[36:37], v131 offset0:99 offset1:107
	ds_read2_b32 v[38:39], v131 offset0:132 offset1:140
	ds_read2_b32 v[40:41], v131 offset0:165 offset1:173
	ds_read2_b32 v[42:43], v131 offset0:198 offset1:206
	ds_read2_b32 v[44:45], v131 offset0:231 offset1:239
	s_mul_hi_i32 s30, s78, 0x2e8ba2e9
	s_lshr_b32 s31, s30, 31
	s_ashr_i32 s30, s30, 5
	s_add_i32 s30, s30, s31
	v_cndmask_b32_e64 v25, v25, 1.0, s[0:1]
	v_cndmask_b32_e64 v24, v24, 1.0, s[0:1]
	v_cndmask_b32_e64 v23, v23, 1.0, s[0:1]
	v_cndmask_b32_e64 v22, v22, 1.0, s[0:1]
	v_cndmask_b32_e64 v27, v21, 1.0, s[0:1]
	v_cndmask_b32_e64 v26, v20, 1.0, s[0:1]
	v_cndmask_b32_e64 v31, v19, 1.0, s[0:1]
	v_cndmask_b32_e64 v30, v18, 1.0, s[0:1]
	s_waitcnt lgkmcnt(7)
	v_mov_b32_e32 v18, v28
	s_waitcnt lgkmcnt(6)
	v_mov_b32_e32 v19, v32
	s_waitcnt lgkmcnt(5)
	v_mov_b32_e32 v20, v34
	s_waitcnt lgkmcnt(4)
	v_mov_b32_e32 v21, v36
	s_mul_i32 s31, s30, 0xb0
	v_pk_mul_f32 v[18:19], v[22:23], v[18:19]
	v_pk_mul_f32 v[20:21], v[24:25], v[20:21]
	s_sub_i32 s82, s78, s31
	v_cvt_pk_bf16_f32 v18, v18, v19
	v_cvt_pk_bf16_f32 v19, v20, v21
	s_waitcnt lgkmcnt(3)
	v_mov_b32_e32 v20, v38
	s_waitcnt lgkmcnt(2)
	v_mov_b32_e32 v21, v40
	s_waitcnt lgkmcnt(1)
	v_mov_b32_e32 v46, v42
	s_waitcnt lgkmcnt(0)
; #define LAS __attribute__((address_space(3)))
; __device__ __forceinline__ unsigned cvtpk(float lo, float hi) { f32x2_t v = {lo, hi}; bf16x2_t b = __builtin_convertvector(v, bf16x2_t); return __builtin_bit_cast(unsigned, b); }
; #define LDS_WAIT() asm volatile("s_waitcnt lgkmcnt(0)" ::: "memory")
; #define CONV_JOB(it_) conv_job<LIST>((it_) < n ? (it_) : n - 1, P)
; __device__ __forceinline__ void conv_emit(const ConvJob& j, int lane, const ConvSet& s, LAS float* scr) {
;     const int k0 = 64 * j.kb; int cnt; (void)vgroup_src(j.kind, j.g, cnt);
;     const int ks = lane >> 3, n4 = (lane & 7) * 4, c = lane & 7; const bool okc = n4 < cnt;
;     const f32x4 one = (f32x4){1.f, 1.f, 1.f, 1.f}; const f32x4 g0 = j.gain ? s.g0 : one, g1 = j.gain ? s.g1 : one;
; #pragma unroll
;     for (int i = 0; i < 8; ++i) { LAS float* sp = scr + (8 * i + ks) * 33 + n4;
; #pragma unroll
;         for (int e = 0; e < 4; ++e) sp[e] = okc ? s.v[i][e] : 0.f; }
;     LDS_WAIT(); asm volatile("" ::: "memory");
; #pragma unroll
;     for (int q = 0; q < 4; ++q) { const int nn = (lane >> 3) + 8 * q; const LAS float* sr = scr + (8 * c) * 33 + nn;
;         u32x4 o; o.x = cvtpk(sr[0 * 33] * g0[0], sr[1 * 33] * g0[1]); o.y = cvtpk(sr[2 * 33] * g0[2], sr[3 * 33] * g0[3]); o.z = cvtpk(sr[4 * 33] * g1[0], sr[5 * 33] * g1[1]); o.w = cvtpk(sr[6 * 33] * g1[2], sr[7 * 33] * g1[3]);
;         *(u32x4*)(j.WT + (size_t)(j.g * 32 + nn) * j.K + k0 + 8 * c) = o; }
;     LDS_WAIT(); asm volatile("" ::: "memory");
; }
; template <int LIST> __device__ __forceinline__ void convert_list(int first, int stride, const Params& P, LAS float* scr, int lane) {
;     ...
;         conv_fetch(CONV_JOB(it + 3 * stride), lane, A); if (it + stride < n) conv_emit(CONV_JOB(it + stride), lane, B, scr);
;         conv_fetch(CONV_JOB(it + 4 * stride), lane, B); if (it + 2 * stride < n) conv_emit(CONV_JOB(it + 2 * stride), lane, C, scr);
;     }
	v_mov_b32_e32 v47, v44
	v_pk_mul_f32 v[20:21], v[30:31], v[20:21]
	v_pk_mul_f32 v[46:47], v[26:27], v[46:47]
	s_lshl_b32 s82, s82, 5
	v_cvt_pk_bf16_f32 v20, v20, v21
	v_cvt_pk_bf16_f32 v21, v46, v47
	v_or_b32_e32 v46, s82, v130
	s_lshl_b32 s30, s30, 6
	v_ashrrev_i32_e32 v47, 31, v46
	s_ashr_i32 s31, s30, 31
	v_lshlrev_b64 v[46:47], 11, v[46:47]
	v_lshl_add_u64 v[46:47], s[50:51], 0, v[46:47]
	s_lshl_b64 s[30:31], s[30:31], 1
	v_lshl_add_u64 v[46:47], v[46:47], 0, s[30:31]
	v_lshl_add_u64 v[46:47], v[46:47], 0, v[126:127]
	v_mov_b32_e32 v32, v29
	v_mov_b32_e32 v36, v35
	global_store_dwordx4 v[46:47], v[18:21], off
	v_mov_b32_e32 v40, v39
	v_mov_b32_e32 v44, v43
	v_pk_mul_f32 v[18:19], v[22:23], v[32:33]
	v_pk_mul_f32 v[20:21], v[24:25], v[36:37]
	v_cvt_pk_bf16_f32 v18, v18, v19
	v_cvt_pk_bf16_f32 v19, v20, v21
	v_pk_mul_f32 v[20:21], v[30:31], v[40:41]
	v_pk_mul_f32 v[28:29], v[26:27], v[44:45]
	v_cvt_pk_bf16_f32 v20, v20, v21
	v_cvt_pk_bf16_f32 v21, v28, v29
	v_or_b32_e32 v28, s82, v133
	v_ashrrev_i32_e32 v29, 31, v28
	v_lshlrev_b64 v[28:29], 11, v[28:29]
	v_lshl_add_u64 v[28:29], s[50:51], 0, v[28:29]
	v_lshl_add_u64 v[28:29], v[28:29], 0, s[30:31]
	v_lshl_add_u64 v[28:29], v[28:29], 0, v[126:127]
	ds_read2_b32 v[32:33], v131 offset0:16 offset1:24
	ds_read2_b32 v[34:35], v131 offset0:49 offset1:57
	global_store_dwordx4 v[28:29], v[18:21], off
	ds_read2_b32 v[28:29], v131 offset0:82 offset1:90
	ds_read2_b32 v[36:37], v131 offset0:115 offset1:123
	ds_read2_b32 v[38:39], v131 offset0:148 offset1:156
	ds_read2_b32 v[40:41], v131 offset0:181 offset1:189
	ds_read2_b32 v[42:43], v131 offset0:214 offset1:222
	ds_read2_b32 v[44:45], v131 offset0:247 offset1:255
	s_waitcnt lgkmcnt(7)
	v_mov_b32_e32 v18, v32
	s_waitcnt lgkmcnt(6)
	v_mov_b32_e32 v19, v34
	s_waitcnt lgkmcnt(5)
	v_mov_b32_e32 v20, v28
	s_waitcnt lgkmcnt(4)
	v_mov_b32_e32 v21, v36
	v_pk_mul_f32 v[18:19], v[22:23], v[18:19]
	v_pk_mul_f32 v[20:21], v[24:25], v[20:21]
	v_cvt_pk_bf16_f32 v18, v18, v19
	v_cvt_pk_bf16_f32 v19, v20, v21
	s_waitcnt lgkmcnt(3)
	v_mov_b32_e32 v20, v38
	s_waitcnt lgkmcnt(2)
	v_mov_b32_e32 v21, v40
	s_waitcnt lgkmcnt(1)
	v_mov_b32_e32 v46, v42
	s_waitcnt lgkmcnt(0)
	v_mov_b32_e32 v47, v44
	v_pk_mul_f32 v[20:21], v[30:31], v[20:21]
	v_pk_mul_f32 v[46:47], v[26:27], v[46:47]
	v_cvt_pk_bf16_f32 v20, v20, v21
	v_cvt_pk_bf16_f32 v21, v46, v47
	v_or_b32_e32 v46, s82, v134
	v_ashrrev_i32_e32 v47, 31, v46
	v_lshlrev_b64 v[46:47], 11, v[46:47]
	v_lshl_add_u64 v[46:47], s[50:51], 0, v[46:47]
	v_lshl_add_u64 v[46:47], v[46:47], 0, s[30:31]
	v_lshl_add_u64 v[46:47], v[46:47], 0, v[126:127]
	v_mov_b32_e32 v34, v33
	v_mov_b32_e32 v36, v29
	global_store_dwordx4 v[46:47], v[18:21], off
	v_mov_b32_e32 v40, v39
	v_mov_b32_e32 v44, v43
	v_pk_mul_f32 v[18:19], v[22:23], v[34:35]
	v_pk_mul_f32 v[20:21], v[24:25], v[36:37]
	v_cvt_pk_bf16_f32 v18, v18, v19
	v_cvt_pk_bf16_f32 v19, v20, v21
	v_pk_mul_f32 v[20:21], v[30:31], v[40:41]
	v_pk_mul_f32 v[22:23], v[26:27], v[44:45]
	v_cvt_pk_bf16_f32 v20, v20, v21
	v_cvt_pk_bf16_f32 v21, v22, v23
	v_or_b32_e32 v22, s82, v135
	v_ashrrev_i32_e32 v23, 31, v22
	v_lshlrev_b64 v[22:23], 11, v[22:23]
	v_lshl_add_u64 v[22:23], s[50:51], 0, v[22:23]
	v_lshl_add_u64 v[22:23], v[22:23], 0, s[30:31]
	v_lshl_add_u64 v[22:23], v[22:23], 0, v[126:127]
	global_store_dwordx4 v[22:23], v[18:21], off
	s_waitcnt lgkmcnt(0)
.LBB0_19:
	s_add_i32 s30, s79, s81
	s_min_i32 s30, s30, 0xaff
	s_mul_hi_i32 s31, s30, 0x2e8ba2e9
	s_lshr_b32 s81, s31, 31
	s_ashr_i32 s31, s31, 5
	s_add_i32 s31, s31, s81
	s_mul_i32 s81, s31, 0xb0
	s_sub_i32 s81, s30, s81
	s_lshl_b32 s30, s31, 6
	s_bfe_i32 s31, s81, 0x10002
	s_lshl_b32 s82, s81, 4
	s_and_b32 s31, s31, 0xb00
	s_and_b32 s82, s82, 0xffffff80
	s_lshl_b32 s81, s81, 5
	s_add_i32 s31, s31, s82
	s_and_b32 s81, s81, 0x60
	s_or_b32 s82, s31, s81
	s_ashr_i32 s31, s30, 31
	s_waitcnt vmcnt(31)
	v_or_b32_e32 v28, s30, v130
	v_mov_b64_e32 v[26:27], s[20:21]
	v_lshl_add_u64 v[18:19], s[30:31], 2, v[124:125]
	v_mad_i64_i32 v[26:27], s[30:31], v28, s24, v[26:27]
	s_ashr_i32 s83, s82, 31
	v_lshl_add_u64 v[26:27], s[82:83], 2, v[26:27]
	s_waitcnt vmcnt(25)
	v_lshl_add_u64 v[50:51], v[26:27], 0, v[122:123]
	v_add_co_u32_e32 v30, vcc, s25, v50
	v_mov_b32_e32 v20, s21
	s_nop 0
	v_addc_co_u32_e32 v31, vcc, 0, v51, vcc
	v_add_co_u32_e32 v34, vcc, s33, v50
	v_cndmask_b32_e64 v23, v19, v20, s[0:1]
	s_nop 0
	v_addc_co_u32_e32 v35, vcc, 0, v51, vcc
	v_add_co_u32_e32 v38, vcc, s34, v50
	v_mov_b32_e32 v19, s20
	s_nop 0
	v_addc_co_u32_e32 v39, vcc, 0, v51, vcc
	v_add_co_u32_e32 v42, vcc, s35, v50
	v_cndmask_b32_e64 v22, v18, v19, s[0:1]
	s_nop 0
	v_addc_co_u32_e32 v43, vcc, 0, v51, vcc
	v_add_co_u32_e32 v46, vcc, 0xdc000, v50
	s_nop 0
	v_addc_co_u32_e32 v47, vcc, 0, v51, vcc
	v_add_co_u32_e32 v52, vcc, 0x108000, v50
	s_nop 0
	v_addc_co_u32_e32 v53, vcc, 0, v51, vcc
	s_waitcnt vmcnt(28)
	v_add_co_u32_e32 v54, vcc, 0x134000, v50
	s_nop 0
	v_addc_co_u32_e32 v55, vcc, 0, v51, vcc
	s_nop 0
	s_nop 0
	s_nop 0
	s_andn2_b64 vcc, exec, s[18:19]
	s_cbranch_vccnz .LBB0_16
; #define LAS __attribute__((address_space(3)))
; __device__ __forceinline__ unsigned cvtpk(float lo, float hi) { f32x2_t v = {lo, hi}; bf16x2_t b = __builtin_convertvector(v, bf16x2_t); return __builtin_bit_cast(unsigned, b); }
; #define LDS_WAIT() asm volatile("s_waitcnt lgkmcnt(0)" ::: "memory")
; #define CONV_JOB(it_) conv_job<LIST>((it_) < n ? (it_) : n - 1, P)
; __device__ __forceinline__ void conv_emit(const ConvJob& j, int lane, const ConvSet& s, LAS float* scr) {
;     const int k0 = 64 * j.kb; int cnt; (void)vgroup_src(j.kind, j.g, cnt);
;     const int ks = lane >> 3, n4 = (lane & 7) * 4, c = lane & 7; const bool okc = n4 < cnt;
;     const f32x4 one = (f32x4){1.f, 1.f, 1.f, 1.f}; const f32x4 g0 = j.gain ? s.g0 : one, g1 = j.gain ? s.g1 : one;
; #pragma unroll
;     for (int i = 0; i < 8; ++i) { LAS float* sp = scr + (8 * i + ks) * 33 + n4;
; #pragma unroll
;         for (int e = 0; e < 4; ++e) sp[e] = okc ? s.v[i][e] : 0.f; }
;     LDS_WAIT(); asm volatile("" ::: "memory");
; #pragma unroll
;     for (int q = 0; q < 4; ++q) { const int nn = (lane >> 3) + 8 * q; const LAS float* sr = scr + (8 * c) * 33 + nn;
;         u32x4 o; o.x = cvtpk(sr[0 * 33] * g0[0], sr[1 * 33] * g0[1]); o.y = cvtpk(sr[2 * 33] * g0[2], sr[3 * 33] * g0[3]); o.z = cvtpk(sr[4 * 33] * g1[0], sr[5 * 33] * g1[1]); o.w = cvtpk(sr[6 * 33] * g1[2], sr[7 * 33] * g1[3]);
;         *(u32x4*)(j.WT + (size_t)(j.g * 32 + nn) * j.K + k0 + 8 * c) = o; }
;     LDS_WAIT(); asm volatile("" ::: "memory");
; }
; template <int LIST> __device__ __forceinline__ void convert_list(int first, int stride, const Params& P, LAS float* scr, int lane) {
;     ...
;         conv_fetch(CONV_JOB(it + 4 * stride), lane, B); if (it + 2 * stride < n) conv_emit(CONV_JOB(it + 2 * stride), lane, C, scr);
	s_waitcnt vmcnt(31)
	ds_write2_b32 v132, v90, v91 offset1:1
	ds_write2_b32 v132, v92, v93 offset0:2 offset1:3
	s_waitcnt vmcnt(30)
	ds_write2_b32 v136, v94, v95 offset1:1
	ds_write2_b32 v137, v96, v97 offset1:1
	s_waitcnt vmcnt(29)
	ds_write2_b32 v138, v98, v99 offset1:1
	ds_write2_b32 v139, v100, v101 offset1:1
	s_waitcnt vmcnt(28)
	ds_write2_b32 v140, v102, v103 offset1:1
	ds_write2_b32 v141, v104, v105 offset1:1
	s_waitcnt vmcnt(27)
	ds_write2_b32 v142, v110, v111 offset1:1
	ds_write2_b32 v143, v112, v113 offset1:1
	s_waitcnt vmcnt(26)
	ds_write2_b32 v144, v106, v107 offset1:1
	ds_write2_b32 v145, v108, v109 offset1:1
	s_waitcnt vmcnt(25)
	ds_write2_b32 v146, v118, v119 offset1:1
	ds_write2_b32 v147, v120, v121 offset1:1
	s_waitcnt vmcnt(24)
	ds_write2_b32 v148, v114, v115 offset1:1
	ds_write2_b32 v149, v116, v117 offset1:1
	s_waitcnt lgkmcnt(0)
	ds_read2_b32 v[92:93], v131 offset1:8
	ds_read2_b32 v[96:97], v131 offset0:33 offset1:41
	ds_read2_b32 v[98:99], v131 offset0:66 offset1:74
	ds_read2_b32 v[100:101], v131 offset0:99 offset1:107
	ds_read2_b32 v[102:103], v131 offset0:132 offset1:140
	ds_read2_b32 v[104:105], v131 offset0:165 offset1:173
	ds_read2_b32 v[106:107], v131 offset0:198 offset1:206
	ds_read2_b32 v[108:109], v131 offset0:231 offset1:239
	s_mul_hi_i32 s18, s80, 0x2e8ba2e9
	s_lshr_b32 s19, s18, 31
	s_ashr_i32 s18, s18, 5
	s_add_i32 s18, s18, s19
	v_cndmask_b32_e64 v89, v89, 1.0, s[0:1]
	v_cndmask_b32_e64 v88, v88, 1.0, s[0:1]
	v_cndmask_b32_e64 v87, v87, 1.0, s[0:1]
	v_cndmask_b32_e64 v86, v86, 1.0, s[0:1]
	v_cndmask_b32_e64 v91, v85, 1.0, s[0:1]
	v_cndmask_b32_e64 v90, v84, 1.0, s[0:1]
	v_cndmask_b32_e64 v95, v83, 1.0, s[0:1]
	v_cndmask_b32_e64 v94, v82, 1.0, s[0:1]
	s_waitcnt lgkmcnt(7)
	v_mov_b32_e32 v82, v92
	s_waitcnt lgkmcnt(6)
	v_mov_b32_e32 v83, v96
	s_waitcnt lgkmcnt(5)
	v_mov_b32_e32 v84, v98
	s_waitcnt lgkmcnt(4)
	v_mov_b32_e32 v85, v100
	s_mul_i32 s19, s18, 0xb0
	v_pk_mul_f32 v[82:83], v[86:87], v[82:83]
	v_pk_mul_f32 v[84:85], v[88:89], v[84:85]
	s_sub_i32 s30, s80, s19
	v_cvt_pk_bf16_f32 v82, v82, v83
	v_cvt_pk_bf16_f32 v83, v84, v85
	s_waitcnt lgkmcnt(3)
	v_mov_b32_e32 v84, v102
	s_waitcnt lgkmcnt(2)
	v_mov_b32_e32 v85, v104
	s_waitcnt lgkmcnt(1)
	v_mov_b32_e32 v110, v106
	s_waitcnt lgkmcnt(0)
	v_mov_b32_e32 v111, v108
	v_pk_mul_f32 v[84:85], v[94:95], v[84:85]
	v_pk_mul_f32 v[110:111], v[90:91], v[110:111]
	s_lshl_b32 s30, s30, 5
	v_cvt_pk_bf16_f32 v84, v84, v85
	v_cvt_pk_bf16_f32 v85, v110, v111
	v_or_b32_e32 v110, s30, v130
	s_lshl_b32 s18, s18, 6
	v_ashrrev_i32_e32 v111, 31, v110
	s_ashr_i32 s19, s18, 31
	v_lshlrev_b64 v[110:111], 11, v[110:111]
	v_lshl_add_u64 v[110:111], s[50:51], 0, v[110:111]
	s_lshl_b64 s[18:19], s[18:19], 1
	v_lshl_add_u64 v[110:111], v[110:111], 0, s[18:19]
	v_mov_b32_e32 v127, v123
	v_lshl_add_u64 v[110:111], v[110:111], 0, v[126:127]
	v_mov_b32_e32 v96, v93
	v_mov_b32_e32 v100, v99
	global_store_dwordx4 v[110:111], v[82:85], off
	v_mov_b32_e32 v104, v103
	v_mov_b32_e32 v108, v107
	v_pk_mul_f32 v[82:83], v[86:87], v[96:97]
	v_pk_mul_f32 v[84:85], v[88:89], v[100:101]
	v_cvt_pk_bf16_f32 v82, v82, v83
	v_cvt_pk_bf16_f32 v83, v84, v85
	v_pk_mul_f32 v[84:85], v[94:95], v[104:105]
	v_pk_mul_f32 v[92:93], v[90:91], v[108:109]
	v_cvt_pk_bf16_f32 v84, v84, v85
	v_cvt_pk_bf16_f32 v85, v92, v93
	v_or_b32_e32 v92, s30, v133
	v_ashrrev_i32_e32 v93, 31, v92
	v_lshlrev_b64 v[92:93], 11, v[92:93]
	v_lshl_add_u64 v[92:93], s[50:51], 0, v[92:93]
	v_lshl_add_u64 v[92:93], v[92:93], 0, s[18:19]
	v_lshl_add_u64 v[92:93], v[92:93], 0, v[126:127]
	ds_read2_b32 v[96:97], v131 offset0:16 offset1:24
	ds_read2_b32 v[98:99], v131 offset0:49 offset1:57
	global_store_dwordx4 v[92:93], v[82:85], off
	ds_read2_b32 v[92:93], v131 offset0:82 offset1:90
	ds_read2_b32 v[100:101], v131 offset0:115 offset1:123
	ds_read2_b32 v[102:103], v131 offset0:148 offset1:156
	ds_read2_b32 v[104:105], v131 offset0:181 offset1:189
	ds_read2_b32 v[106:107], v131 offset0:214 offset1:222
	ds_read2_b32 v[108:109], v131 offset0:247 offset1:255
	s_waitcnt lgkmcnt(7)
	v_mov_b32_e32 v82, v96
	s_waitcnt lgkmcnt(6)
	v_mov_b32_e32 v83, v98
	s_waitcnt lgkmcnt(5)
	v_mov_b32_e32 v84, v92
	s_waitcnt lgkmcnt(4)
	v_mov_b32_e32 v85, v100
	v_pk_mul_f32 v[82:83], v[86:87], v[82:83]
	v_pk_mul_f32 v[84:85], v[88:89], v[84:85]
	v_cvt_pk_bf16_f32 v82, v82, v83
	v_cvt_pk_bf16_f32 v83, v84, v85
	s_waitcnt lgkmcnt(3)
	v_mov_b32_e32 v84, v102
	s_waitcnt lgkmcnt(2)
	v_mov_b32_e32 v85, v104
	s_waitcnt lgkmcnt(1)
	v_mov_b32_e32 v110, v106
	s_waitcnt lgkmcnt(0)
	v_mov_b32_e32 v111, v108
	v_pk_mul_f32 v[84:85], v[94:95], v[84:85]
	v_pk_mul_f32 v[110:111], v[90:91], v[110:111]
	v_cvt_pk_bf16_f32 v84, v84, v85
	v_cvt_pk_bf16_f32 v85, v110, v111
	v_or_b32_e32 v110, s30, v134
	v_ashrrev_i32_e32 v111, 31, v110
	v_lshlrev_b64 v[110:111], 11, v[110:111]
	v_lshl_add_u64 v[110:111], s[50:51], 0, v[110:111]
	v_lshl_add_u64 v[110:111], v[110:111], 0, s[18:19]
	v_lshl_add_u64 v[110:111], v[110:111], 0, v[126:127]
	v_mov_b32_e32 v98, v97
	v_mov_b32_e32 v100, v93
	global_store_dwordx4 v[110:111], v[82:85], off
	v_mov_b32_e32 v104, v103
	v_mov_b32_e32 v108, v107
	v_pk_mul_f32 v[82:83], v[86:87], v[98:99]
	v_pk_mul_f32 v[84:85], v[88:89], v[100:101]
	v_cvt_pk_bf16_f32 v82, v82, v83
	v_cvt_pk_bf16_f32 v83, v84, v85
	v_pk_mul_f32 v[84:85], v[94:95], v[104:105]
	v_pk_mul_f32 v[86:87], v[90:91], v[108:109]
	v_cvt_pk_bf16_f32 v84, v84, v85
	v_cvt_pk_bf16_f32 v85, v86, v87
	v_or_b32_e32 v86, s30, v135
	v_ashrrev_i32_e32 v87, 31, v86
	v_lshlrev_b64 v[86:87], 11, v[86:87]
	v_lshl_add_u64 v[86:87], s[50:51], 0, v[86:87]
	v_lshl_add_u64 v[86:87], v[86:87], 0, s[18:19]
	v_lshl_add_u64 v[86:87], v[86:87], 0, v[126:127]
	global_store_dwordx4 v[86:87], v[82:85], off
	s_waitcnt lgkmcnt(0)
	s_branch .LBB0_16
